# P3 scan: next step's operands prefetched a full step ahead into free AGPRs, copied to VGPRs at step end; selection tail waits only for prefetch loads
# speedup vs baseline: 1.2371x; 1.0083x over previous
; __device__ __forceinline__ void seq_item(const Params& p, int item, char* smem, const bool write_o = true) {
;     ...
;   const int m = 1 - (item >> 7); const int rem = item & 127; const int bh = rem >> 2, sl = rem & 3; const int b = bh >> 2, h = bh & 3;
;   char* ws = p.ws;
;   u16* STs = (u16*)smem;
;   u16* VTs = (u16*)(smem + 8704);
;   const int r = lane & 31, hh = (lane >> 5) * 8;
;   const int dcol = w * 32 + r;
;   u16* Om = (u16*)(ws + OFF_O) + (size_t)m * NT * 512;
;   float* SSQO = (float*)(ws + OFF_SSQO) + (size_t)m * NT * 16;
;   const float* DVEC = (const float*)(ws + OFF_DVEC);
;   f32x16 S = zero16();
;   __syncthreads();
;   uint4 vt4; bf16x8 ktf[4], pnf[8], qbf[8]; float dvn; u16 o0[16];
;     ...
;   SEQ_LOADS(0)
.LBB0_1019:
	s_or_b64 exec, exec, s[22:23]
	s_and_b32 s2, s37, 3
	s_lshl_b32 s21, s2, 2
	s_and_b32 s2, s49, 31
	s_lshl_b32 s22, s2, 5
	s_lshl_b32 s2, s2, 20
	s_lshl_b32 s20, s54, 4
	v_lshl_add_u64 v[66:67], v[50:51], 0, s[2:3]
	s_mul_hi_u32 s2, s48, 0x108000
	s_mul_i32 s48, s48, 0x108000
	s_add_u32 s23, s28, s48
	s_addc_u32 s24, s29, s2
	v_lshlrev_b64 v[2:3], 1, v[2:3]
	v_lshlrev_b32_e32 v0, 6, v4
	v_lshl_add_u64 v[4:5], s[18:19], 0, v[2:3]
	s_add_u32 s18, s23, s20
	s_addc_u32 s19, s24, 0
	s_lshl_b32 s23, s47, 2
	v_lshlrev_b32_e32 v0, 1, v0
	s_add_u32 s18, s18, s23
	v_lshl_add_u64 v[68:69], v[44:45], 0, v[0:1]
	v_lshlrev_b32_e32 v0, 1, v60
	s_addc_u32 s19, s19, 0
	v_lshl_add_u64 v[6:7], s[0:1], 0, v[0:1]
	s_add_u32 s0, s30, s21
	s_addc_u32 s1, s31, 0
	v_lshl_add_u64 v[4:5], v[4:5], 0, v[0:1]
	v_mov_b32_e32 v63, v1
	s_add_u32 s0, s0, s20
	v_lshl_add_u64 v[70:71], v[4:5], 0, v[54:55]
	v_lshlrev_b64 v[4:5], 10, v[62:63]
	v_lshl_add_u64 v[2:3], v[6:7], 0, v[2:3]
	s_addc_u32 s1, s1, 0
	v_lshl_add_u64 v[4:5], v[2:3], 0, v[4:5]
	s_add_u32 s0, s0, s48
	v_lshl_add_u64 v[72:73], v[46:47], 0, v[4:5]
	v_lshlrev_b64 v[4:5], 6, v[62:63]
	s_addc_u32 s1, s1, s2
	v_lshl_add_u64 v[74:75], s[0:1], 0, v[4:5]
	s_lshl_b32 s0, s46, 10
	v_lshl_add_u64 v[2:3], v[2:3], 0, v[64:65]
	v_mov_b32_e32 v0, v1
	s_sub_i32 s0, s22, s0
	v_lshl_add_u64 v[76:77], v[48:49], 0, v[2:3]
	v_mov_b32_e32 v2, v1
	v_mov_b32_e32 v3, v1
	v_mov_b32_e32 v4, v1
	v_mov_b32_e32 v5, v1
	v_mov_b32_e32 v6, v1
	v_mov_b32_e32 v7, v1
	v_mov_b32_e32 v8, v1
	v_mov_b32_e32 v9, v1
	v_mov_b32_e32 v10, v1
	v_mov_b32_e32 v11, v1
	v_mov_b32_e32 v12, v1
	v_mov_b32_e32 v13, v1
	v_mov_b32_e32 v14, v1
	v_mov_b32_e32 v15, v1
	v_accvgpr_write_b32 a0, v0
	s_add_i32 s20, s0, 0x401
	v_accvgpr_write_b32 a1, v1
	v_accvgpr_write_b32 a2, v2
	v_accvgpr_write_b32 a3, v3
	v_accvgpr_write_b32 a4, v4
	v_accvgpr_write_b32 a5, v5
	v_accvgpr_write_b32 a6, v6
	v_accvgpr_write_b32 a7, v7
	v_accvgpr_write_b32 a8, v8
	v_accvgpr_write_b32 a9, v9
	v_accvgpr_write_b32 a10, v10
	v_accvgpr_write_b32 a11, v11
	v_accvgpr_write_b32 a12, v12
	v_accvgpr_write_b32 a13, v13
	v_accvgpr_write_b32 a14, v14
	v_accvgpr_write_b32 a15, v15
	s_mov_b64 s[22:23], 0
	s_waitcnt vmcnt(0)
	s_branch .LBB0_1022

; __device__ __forceinline__ u16 f2bf(float f) { return (u16)(pack2(f, f) & 0xffffu); }
; __device__ __forceinline__ int rowmap(int e, int lane) { return (e & 3) + 8 * (e >> 2) + 4 * (lane >> 5); }
; __device__ __forceinline__ void seq_item(const Params& p, int item, char* smem, const bool write_o = true) {
;     ...
;   for (int n = 0; n < 32; n++) {
; #pragma unroll
;     for (int e = 0; e < 16; e++) STs[rowmap(e, lane) * 136 + dcol] = f2bf(S[e]);
;     *(uint4*)&VTs[(tid >> 3) * 72 + (tid & 7) * 8] = vt4;
;     __syncthreads();
.LBB0_1022:
	s_nop 0
	v_accvgpr_read_b32 v17, a15
	v_accvgpr_read_b32 v2, a0
	v_accvgpr_read_b32 v3, a1
	v_cvt_pk_bf16_f32 v0, v2, s0
	v_accvgpr_read_b32 v4, a2
	ds_write_b16 v82, v0
	v_cvt_pk_bf16_f32 v0, v3, s0
	v_accvgpr_read_b32 v5, a3
	ds_write_b16 v82, v0 offset:272
	v_cvt_pk_bf16_f32 v0, v4, s0
	v_accvgpr_read_b32 v6, a4
	ds_write_b16 v82, v0 offset:544
	v_cvt_pk_bf16_f32 v0, v5, s0
	v_accvgpr_read_b32 v7, a5
	ds_write_b16 v82, v0 offset:816
	v_cvt_pk_bf16_f32 v0, v6, s0
	v_accvgpr_read_b32 v8, a6
	ds_write_b16 v82, v0 offset:2176
	v_cvt_pk_bf16_f32 v0, v7, s0
	v_accvgpr_read_b32 v9, a7
	ds_write_b16 v82, v0 offset:2448
	v_cvt_pk_bf16_f32 v0, v8, s0
	v_accvgpr_read_b32 v10, a8
	ds_write_b16 v82, v0 offset:2720
	v_cvt_pk_bf16_f32 v0, v9, s0
	v_accvgpr_read_b32 v11, a9
	ds_write_b16 v82, v0 offset:2992
	v_cvt_pk_bf16_f32 v0, v10, s0
	v_accvgpr_read_b32 v12, a10
	ds_write_b16 v82, v0 offset:4352
	v_cvt_pk_bf16_f32 v0, v11, s0
	v_accvgpr_read_b32 v13, a11
	ds_write_b16 v82, v0 offset:4624
	v_cvt_pk_bf16_f32 v0, v12, s0
	v_accvgpr_read_b32 v14, a12
	ds_write_b16 v82, v0 offset:4896
	v_cvt_pk_bf16_f32 v0, v13, s0
	v_accvgpr_read_b32 v15, a13
	ds_write_b16 v82, v0 offset:5168
	v_cvt_pk_bf16_f32 v0, v14, s0
	v_accvgpr_read_b32 v16, a14
	ds_write_b16 v82, v0 offset:6528
	v_cvt_pk_bf16_f32 v0, v15, s0
	ds_write_b16 v82, v0 offset:6800
	v_cvt_pk_bf16_f32 v0, v16, s0
	ds_write_b16 v82, v0 offset:7072
	v_cvt_pk_bf16_f32 v0, v17, s0
	ds_write_b16 v82, v0 offset:7344
	s_waitcnt vmcnt(5)
	ds_write_b128 v59, v[102:105] offset:8704
	s_waitcnt lgkmcnt(0)
	s_barrier
	s_cmp_eq_u32 s22, 0x1f0000
	s_cbranch_scc1 .Lp3_pf_done
	s_ashr_i32 s21, s20, 31
	s_lshl_b64 s[24:25], s[20:21], 14
	v_lshl_add_u64 v[102:103], v[68:69], 0, s[24:25]
	s_lshl_b64 s[48:49], s[20:21], 9
	v_lshl_add_u64 v[104:105], v[36:37], 0, s[48:49]
	global_load_dwordx4 a[144:147], v[102:103], off
	global_load_dword a148, v[104:105], off
	v_lshl_add_u64 v[102:103], v[38:39], 0, s[24:25]
	global_load_dwordx4 a[150:153], v[102:103], off
	global_load_dwordx4 a[154:157], v[102:103], off offset:32
	global_load_dwordx4 a[158:161], v[102:103], off offset:64
	global_load_dwordx4 a[162:165], v[102:103], off offset:96
	s_and_b64 s[48:49], exec, s[16:17]
	s_cbranch_scc0 .Lp3_pf_nopn
	global_load_dwordx4 a[166:169], v[66:67], off offset:-128
	global_load_dwordx4 a[170:173], v[66:67], off offset:-96
	global_load_dwordx4 a[174:177], v[66:67], off offset:-64
	global_load_dwordx4 a[178:181], v[66:67], off offset:-32
	global_load_dwordx4 a[182:185], v[66:67], off
	global_load_dwordx4 a[186:189], v[66:67], off offset:32
	global_load_dwordx4 a[190:193], v[66:67], off offset:64
	global_load_dwordx4 a[194:197], v[66:67], off offset:96
.Lp3_pf_nopn:
	s_and_b64 s[48:49], exec, s[4:5]
	s_cbranch_scc0 .Lp3_pf_done
	s_lshl_b64 s[24:25], s[20:21], 13
	v_lshl_add_u64 v[102:103], s[24:25], 1, v[42:43]
	global_load_dwordx4 a[198:201], v[102:103], off
	global_load_dwordx4 a[202:205], v[102:103], off offset:32
	global_load_dwordx4 a[206:209], v[102:103], off offset:64
	global_load_dwordx4 a[210:213], v[102:103], off offset:96
	global_load_dwordx4 a[214:217], v[102:103], off offset:128
	global_load_dwordx4 a[218:221], v[102:103], off offset:160
	global_load_dwordx4 a[222:225], v[102:103], off offset:192
	global_load_dwordx4 a[226:229], v[102:103], off offset:224
	s_add_u32 s24, s22, 0x10000
	v_add_u32_e32 v18, s24, v64
	v_lshl_add_u64 v[102:103], v[76:77], 0, s[22:23]
	global_load_ushort a230, v[102:103], off
	v_or_b32_e32 v0, 0x400, v18
	v_lshl_add_u64 v[102:103], v[70:71], 0, v[0:1]
	global_load_ushort a231, v[102:103], off
	v_or_b32_e32 v0, 0x800, v18
	v_lshl_add_u64 v[104:105], v[70:71], 0, v[0:1]
	global_load_ushort a232, v[104:105], off
	v_or_b32_e32 v0, 0xc00, v18
	v_lshl_add_u64 v[102:103], v[70:71], 0, v[0:1]
	global_load_ushort a233, v[102:103], off
	v_or_b32_e32 v0, 0x2000, v18
	v_lshl_add_u64 v[104:105], v[70:71], 0, v[0:1]
	global_load_ushort a234, v[104:105], off
	v_or_b32_e32 v0, 0x2400, v18
	v_lshl_add_u64 v[102:103], v[70:71], 0, v[0:1]
	global_load_ushort a235, v[102:103], off
	v_or_b32_e32 v0, 0x2800, v18
	v_lshl_add_u64 v[104:105], v[70:71], 0, v[0:1]
	global_load_ushort a236, v[104:105], off
	v_or_b32_e32 v0, 0x2c00, v18
	v_lshl_add_u64 v[102:103], v[70:71], 0, v[0:1]
	global_load_ushort a237, v[102:103], off
	v_or_b32_e32 v0, 0x4000, v18
	v_lshl_add_u64 v[104:105], v[70:71], 0, v[0:1]
	global_load_ushort a238, v[104:105], off
	v_or_b32_e32 v0, 0x4400, v18
	v_lshl_add_u64 v[102:103], v[70:71], 0, v[0:1]
	global_load_ushort a239, v[102:103], off
	v_or_b32_e32 v0, 0x4800, v18
	v_lshl_add_u64 v[104:105], v[70:71], 0, v[0:1]
	global_load_ushort a240, v[104:105], off
	v_or_b32_e32 v0, 0x4c00, v18
	v_lshl_add_u64 v[102:103], v[70:71], 0, v[0:1]
	global_load_ushort a241, v[102:103], off
	v_or_b32_e32 v0, 0x6000, v18
	v_lshl_add_u64 v[104:105], v[70:71], 0, v[0:1]
	global_load_ushort a242, v[104:105], off
	v_or_b32_e32 v0, 0x6400, v18
	v_lshl_add_u64 v[102:103], v[70:71], 0, v[0:1]
	global_load_ushort a243, v[102:103], off
	v_or_b32_e32 v0, 0x6800, v18
	v_lshl_add_u64 v[104:105], v[70:71], 0, v[0:1]
	global_load_ushort a244, v[104:105], off
	v_or_b32_e32 v0, 0x6c00, v18
	v_lshl_add_u64 v[102:103], v[70:71], 0, v[0:1]
	global_load_ushort a245, v[102:103], off
; __device__ __forceinline__ float bf2f(u16 h) { return __uint_as_float(((unsigned)h) << 16); }
; __device__ __forceinline__ void seq_item(const Params& p, int item, char* smem, const bool write_o = true) {
;     ...
;     if (w < 2) {
;       f32x16 o;
; #pragma unroll
;       for (int e = 0; e < 16; e++) o[e] = bf2f(o0[e]);
; #pragma unroll
;       for (int ks = 0; ks < 8; ks++) {
;         bf16x8 bb = *(const bf16x8*)&STs[r * 136 + ks * 16 + hh];
;         o = mfma16(qbf[ks], bb, o);
;       }
.Lp3_pf_done:
	s_and_saveexec_b64 s[0:1], s[4:5]
	s_cbranch_execz .LBB0_1055
	ds_read_b128 v[18:21], v83
	ds_read_b128 v[22:25], v83 offset:32
	v_lshlrev_b32_e32 v0, 16, v57
	v_lshlrev_b32_e32 v26, 16, v61
	v_lshlrev_b32_e32 v27, 16, v87
	v_lshlrev_b32_e32 v28, 16, v88
	v_lshlrev_b32_e32 v29, 16, v89
	v_lshlrev_b32_e32 v30, 16, v90
	v_lshlrev_b32_e32 v31, 16, v91
	v_lshlrev_b32_e32 v32, 16, v92
	v_lshlrev_b32_e32 v33, 16, v93
	v_lshlrev_b32_e32 v63, 16, v94
	v_lshlrev_b32_e32 v65, 16, v95
	v_lshlrev_b32_e32 v78, 16, v96
	v_lshlrev_b32_e32 v79, 16, v97
	v_lshlrev_b32_e32 v101, 16, v98
	v_lshlrev_b32_e32 v186, 16, v99
	v_lshlrev_b32_e32 v187, 16, v100
	v_accvgpr_write_b32 a0, v0
	v_accvgpr_write_b32 a1, v26
	v_accvgpr_write_b32 a2, v27
	v_accvgpr_write_b32 a3, v28
	v_accvgpr_write_b32 a4, v29
	v_accvgpr_write_b32 a5, v30
	v_accvgpr_write_b32 a6, v31
	v_accvgpr_write_b32 a7, v32
	v_accvgpr_write_b32 a8, v33
	v_accvgpr_write_b32 a9, v63
	v_accvgpr_write_b32 a10, v65
	v_accvgpr_write_b32 a11, v78
	v_accvgpr_write_b32 a12, v79
	v_accvgpr_write_b32 a13, v101
	v_accvgpr_write_b32 a14, v186
	v_accvgpr_write_b32 a15, v187
	v_cmp_lt_i32_e32 vcc, v85, v86
	v_lshl_add_u64 v[78:79], v[72:73], 0, s[22:23]
	s_waitcnt lgkmcnt(1)
	v_mfma_f32_32x32x16_bf16 a[0:15], v[154:157], v[18:21], a[0:15]
	v_cndmask_b32_e32 v0, v84, v85, vcc
	v_lshlrev_b32_e32 v63, 2, v0
	s_waitcnt lgkmcnt(0)
	v_mfma_f32_32x32x16_bf16 a[0:15], v[158:161], v[22:25], a[0:15]
	ds_read_b128 v[18:21], v83 offset:64
	ds_read_b128 v[22:25], v83 offset:96
	s_waitcnt lgkmcnt(1)
	v_mfma_f32_32x32x16_bf16 a[0:15], v[162:165], v[18:21], a[0:15]
	s_waitcnt lgkmcnt(0)
	v_mfma_f32_32x32x16_bf16 a[0:15], v[166:169], v[22:25], a[0:15]
	ds_read_b128 v[18:21], v83 offset:128
	ds_read_b128 v[22:25], v83 offset:160
	s_waitcnt lgkmcnt(1)
	v_mfma_f32_32x32x16_bf16 a[0:15], v[170:173], v[18:21], a[0:15]
	s_waitcnt lgkmcnt(0)
	v_mfma_f32_32x32x16_bf16 a[0:15], v[174:177], v[22:25], a[0:15]
	ds_read_b128 v[18:21], v83 offset:192
	ds_read_b128 v[22:25], v83 offset:224
	s_waitcnt lgkmcnt(1)
	v_mfma_f32_32x32x16_bf16 a[0:15], v[178:181], v[18:21], a[0:15]
	v_add_co_u32_e32 v20, vcc, s35, v78
	s_nop 1
	v_addc_co_u32_e32 v21, vcc, 0, v79, vcc
	s_waitcnt lgkmcnt(0)
	v_mfma_f32_32x32x16_bf16 a[0:15], v[182:185], v[22:25], a[0:15]
	s_nop 11
	v_accvgpr_read_b32 v18, a0
	v_accvgpr_read_b32 v19, a1
	v_accvgpr_read_b32 v20, a2
	v_accvgpr_read_b32 v21, a3
	v_accvgpr_read_b32 v22, a4
	v_accvgpr_read_b32 v23, a5
	v_accvgpr_read_b32 v24, a6
	v_accvgpr_read_b32 v25, a7
	v_accvgpr_read_b32 v26, a8
	v_accvgpr_read_b32 v27, a9
	v_accvgpr_read_b32 v28, a10
	v_accvgpr_read_b32 v29, a11
	v_accvgpr_read_b32 v30, a12
	v_accvgpr_read_b32 v31, a13
	v_accvgpr_read_b32 v32, a14
	v_accvgpr_read_b32 v33, a15
	v_mul_f32_e32 v57, v18, v18
	v_mul_f32_e32 v61, v19, v19
	v_mul_f32_e32 v87, v20, v20
	v_mul_f32_e32 v88, v21, v21
	v_mul_f32_e32 v89, v22, v22
	v_mul_f32_e32 v90, v23, v23
	v_mul_f32_e32 v91, v24, v24
	v_mul_f32_e32 v92, v25, v25
	v_mul_f32_e32 v93, v26, v26
	v_mul_f32_e32 v94, v27, v27
	v_mul_f32_e32 v95, v28, v28
	v_mul_f32_e32 v96, v29, v29
	v_mul_f32_e32 v97, v30, v30
	v_mul_f32_e32 v98, v31, v31
	v_mul_f32_e32 v99, v32, v32
	v_mul_f32_e32 v100, v33, v33
	v_mov_b32_dpp v57, v57 quad_perm:[1,0,3,2] row_mask:0xf bank_mask:0xf bound_ctrl:1
	v_mov_b32_dpp v61, v61 quad_perm:[1,0,3,2] row_mask:0xf bank_mask:0xf bound_ctrl:1
	v_mov_b32_dpp v87, v87 quad_perm:[1,0,3,2] row_mask:0xf bank_mask:0xf bound_ctrl:1
	v_mov_b32_dpp v88, v88 quad_perm:[1,0,3,2] row_mask:0xf bank_mask:0xf bound_ctrl:1
	v_mov_b32_dpp v89, v89 quad_perm:[1,0,3,2] row_mask:0xf bank_mask:0xf bound_ctrl:1
	v_mov_b32_dpp v90, v90 quad_perm:[1,0,3,2] row_mask:0xf bank_mask:0xf bound_ctrl:1
	v_mov_b32_dpp v91, v91 quad_perm:[1,0,3,2] row_mask:0xf bank_mask:0xf bound_ctrl:1
	v_mov_b32_dpp v92, v92 quad_perm:[1,0,3,2] row_mask:0xf bank_mask:0xf bound_ctrl:1
	v_mov_b32_dpp v93, v93 quad_perm:[1,0,3,2] row_mask:0xf bank_mask:0xf bound_ctrl:1
	v_mov_b32_dpp v94, v94 quad_perm:[1,0,3,2] row_mask:0xf bank_mask:0xf bound_ctrl:1
	v_mov_b32_dpp v95, v95 quad_perm:[1,0,3,2] row_mask:0xf bank_mask:0xf bound_ctrl:1
	v_mov_b32_dpp v96, v96 quad_perm:[1,0,3,2] row_mask:0xf bank_mask:0xf bound_ctrl:1
	v_mov_b32_dpp v97, v97 quad_perm:[1,0,3,2] row_mask:0xf bank_mask:0xf bound_ctrl:1
	v_mov_b32_dpp v98, v98 quad_perm:[1,0,3,2] row_mask:0xf bank_mask:0xf bound_ctrl:1
	v_mov_b32_dpp v99, v99 quad_perm:[1,0,3,2] row_mask:0xf bank_mask:0xf bound_ctrl:1
	v_mov_b32_dpp v100, v100 quad_perm:[1,0,3,2] row_mask:0xf bank_mask:0xf bound_ctrl:1
	v_fmac_f32_e32 v57, v18, v18
	v_fmac_f32_e32 v61, v19, v19
	v_fmac_f32_e32 v87, v20, v20
	v_fmac_f32_e32 v88, v21, v21
	v_fmac_f32_e32 v89, v22, v22
	v_fmac_f32_e32 v90, v23, v23
	v_fmac_f32_e32 v91, v24, v24
	v_fmac_f32_e32 v92, v25, v25
	v_fmac_f32_e32 v93, v26, v26
	v_fmac_f32_e32 v94, v27, v27
	v_fmac_f32_e32 v95, v28, v28
	v_fmac_f32_e32 v96, v29, v29
	v_fmac_f32_e32 v97, v30, v30
	v_fmac_f32_e32 v98, v31, v31
	v_fmac_f32_e32 v99, v32, v32
	v_fmac_f32_e32 v100, v33, v33
	v_add_f32_dpp v57, v57, v57 quad_perm:[2,3,0,1] row_mask:0xf bank_mask:0xf bound_ctrl:1
	v_add_f32_dpp v61, v61, v61 quad_perm:[2,3,0,1] row_mask:0xf bank_mask:0xf bound_ctrl:1
	v_add_f32_dpp v87, v87, v87 quad_perm:[2,3,0,1] row_mask:0xf bank_mask:0xf bound_ctrl:1
	v_add_f32_dpp v88, v88, v88 quad_perm:[2,3,0,1] row_mask:0xf bank_mask:0xf bound_ctrl:1
	v_add_f32_dpp v89, v89, v89 quad_perm:[2,3,0,1] row_mask:0xf bank_mask:0xf bound_ctrl:1
	v_add_f32_dpp v90, v90, v90 quad_perm:[2,3,0,1] row_mask:0xf bank_mask:0xf bound_ctrl:1
	v_add_f32_dpp v91, v91, v91 quad_perm:[2,3,0,1] row_mask:0xf bank_mask:0xf bound_ctrl:1
; __device__ __forceinline__ u16 f2bf(float f) { return (u16)(pack2(f, f) & 0xffffu); }
; __device__ __forceinline__ float sum32(float v) { v = dpp_row_sum16(v); v += __shfl_xor(v, 16); return v; }
; __device__ __forceinline__ int rowmap(int e, int lane) { return (e & 3) + 8 * (e >> 2) + 4 * (lane >> 5); }
; __device__ __forceinline__ void seq_item(const Params& p, int item, char* smem, const bool write_o = true) {
;     ...
; #pragma unroll
;       for (int e = 0; e < 16; e++) {
;         const int t = w * 32 + rowmap(e, lane);
;         if (write_o) Om[(size_t)(tok0 + t) * 512 + h * 128 + sl * 32 + r] = f2bf(o[e]);
;         float sq = sum32(o[e] * o[e]);
;         if (r == 0) SSQO[((size_t)(tok0 + t) * 4 + h) * 4 + sl] = sq;
;       }
	v_add_f32_dpp v92, v92, v92 quad_perm:[2,3,0,1] row_mask:0xf bank_mask:0xf bound_ctrl:1
	v_add_f32_dpp v93, v93, v93 quad_perm:[2,3,0,1] row_mask:0xf bank_mask:0xf bound_ctrl:1
	v_add_f32_dpp v94, v94, v94 quad_perm:[2,3,0,1] row_mask:0xf bank_mask:0xf bound_ctrl:1
	v_add_f32_dpp v95, v95, v95 quad_perm:[2,3,0,1] row_mask:0xf bank_mask:0xf bound_ctrl:1
	v_add_f32_dpp v96, v96, v96 quad_perm:[2,3,0,1] row_mask:0xf bank_mask:0xf bound_ctrl:1
	v_add_f32_dpp v97, v97, v97 quad_perm:[2,3,0,1] row_mask:0xf bank_mask:0xf bound_ctrl:1
	v_add_f32_dpp v98, v98, v98 quad_perm:[2,3,0,1] row_mask:0xf bank_mask:0xf bound_ctrl:1
	v_add_f32_dpp v99, v99, v99 quad_perm:[2,3,0,1] row_mask:0xf bank_mask:0xf bound_ctrl:1
	v_add_f32_dpp v100, v100, v100 quad_perm:[2,3,0,1] row_mask:0xf bank_mask:0xf bound_ctrl:1
	v_add_f32_dpp v57, v57, v57 row_half_mirror row_mask:0xf bank_mask:0xf bound_ctrl:1
	v_add_f32_dpp v61, v61, v61 row_half_mirror row_mask:0xf bank_mask:0xf bound_ctrl:1
	v_add_f32_dpp v87, v87, v87 row_half_mirror row_mask:0xf bank_mask:0xf bound_ctrl:1
	v_add_f32_dpp v88, v88, v88 row_half_mirror row_mask:0xf bank_mask:0xf bound_ctrl:1
	v_add_f32_dpp v89, v89, v89 row_half_mirror row_mask:0xf bank_mask:0xf bound_ctrl:1
	v_add_f32_dpp v90, v90, v90 row_half_mirror row_mask:0xf bank_mask:0xf bound_ctrl:1
	v_add_f32_dpp v91, v91, v91 row_half_mirror row_mask:0xf bank_mask:0xf bound_ctrl:1
	v_add_f32_dpp v92, v92, v92 row_half_mirror row_mask:0xf bank_mask:0xf bound_ctrl:1
	v_add_f32_dpp v93, v93, v93 row_half_mirror row_mask:0xf bank_mask:0xf bound_ctrl:1
	v_add_f32_dpp v94, v94, v94 row_half_mirror row_mask:0xf bank_mask:0xf bound_ctrl:1
	v_add_f32_dpp v95, v95, v95 row_half_mirror row_mask:0xf bank_mask:0xf bound_ctrl:1
	v_add_f32_dpp v96, v96, v96 row_half_mirror row_mask:0xf bank_mask:0xf bound_ctrl:1
	v_add_f32_dpp v97, v97, v97 row_half_mirror row_mask:0xf bank_mask:0xf bound_ctrl:1
	v_add_f32_dpp v98, v98, v98 row_half_mirror row_mask:0xf bank_mask:0xf bound_ctrl:1
	v_add_f32_dpp v99, v99, v99 row_half_mirror row_mask:0xf bank_mask:0xf bound_ctrl:1
	v_add_f32_dpp v100, v100, v100 row_half_mirror row_mask:0xf bank_mask:0xf bound_ctrl:1
	v_add_f32_dpp v57, v57, v57 row_mirror row_mask:0xf bank_mask:0xf bound_ctrl:1
	v_add_f32_dpp v61, v61, v61 row_mirror row_mask:0xf bank_mask:0xf bound_ctrl:1
	v_add_f32_dpp v87, v87, v87 row_mirror row_mask:0xf bank_mask:0xf bound_ctrl:1
	v_add_f32_dpp v88, v88, v88 row_mirror row_mask:0xf bank_mask:0xf bound_ctrl:1
	v_add_f32_dpp v89, v89, v89 row_mirror row_mask:0xf bank_mask:0xf bound_ctrl:1
	v_add_f32_dpp v90, v90, v90 row_mirror row_mask:0xf bank_mask:0xf bound_ctrl:1
	v_add_f32_dpp v91, v91, v91 row_mirror row_mask:0xf bank_mask:0xf bound_ctrl:1
	v_add_f32_dpp v92, v92, v92 row_mirror row_mask:0xf bank_mask:0xf bound_ctrl:1
	v_add_f32_dpp v93, v93, v93 row_mirror row_mask:0xf bank_mask:0xf bound_ctrl:1
	v_add_f32_dpp v94, v94, v94 row_mirror row_mask:0xf bank_mask:0xf bound_ctrl:1
	v_add_f32_dpp v95, v95, v95 row_mirror row_mask:0xf bank_mask:0xf bound_ctrl:1
	v_add_f32_dpp v96, v96, v96 row_mirror row_mask:0xf bank_mask:0xf bound_ctrl:1
	v_add_f32_dpp v97, v97, v97 row_mirror row_mask:0xf bank_mask:0xf bound_ctrl:1
	v_add_f32_dpp v98, v98, v98 row_mirror row_mask:0xf bank_mask:0xf bound_ctrl:1
	v_add_f32_dpp v99, v99, v99 row_mirror row_mask:0xf bank_mask:0xf bound_ctrl:1
	v_add_f32_dpp v100, v100, v100 row_mirror row_mask:0xf bank_mask:0xf bound_ctrl:1
	v_mov_b32_e32 v0, v62
	v_lshlrev_b64 v[78:79], 10, v[0:1]
	v_lshl_add_u64 v[78:79], v[70:71], 0, v[78:79]
	v_cvt_pk_bf16_f32 v18, v18, v18
	v_cvt_pk_bf16_f32 v19, v19, v19
	v_cvt_pk_bf16_f32 v20, v20, v20
	v_cvt_pk_bf16_f32 v21, v21, v21
	global_store_short v[78:79], v18, off
	global_store_short v[78:79], v19, off offset:1024
	global_store_short v[78:79], v20, off offset:2048
	global_store_short v[78:79], v21, off offset:3072
	v_or_b32_e32 v0, 8, v62
	v_lshlrev_b64 v[78:79], 10, v[0:1]
	v_lshl_add_u64 v[78:79], v[70:71], 0, v[78:79]
	v_cvt_pk_bf16_f32 v22, v22, v22
	v_cvt_pk_bf16_f32 v23, v23, v23
	v_cvt_pk_bf16_f32 v24, v24, v24
	v_cvt_pk_bf16_f32 v25, v25, v25
	global_store_short v[78:79], v22, off
	global_store_short v[78:79], v23, off offset:1024
	global_store_short v[78:79], v24, off offset:2048
	global_store_short v[78:79], v25, off offset:3072
	v_or_b32_e32 v0, 16, v62
	v_lshlrev_b64 v[78:79], 10, v[0:1]
	v_lshl_add_u64 v[78:79], v[70:71], 0, v[78:79]
	v_cvt_pk_bf16_f32 v26, v26, v26
	v_cvt_pk_bf16_f32 v27, v27, v27
	v_cvt_pk_bf16_f32 v28, v28, v28
	v_cvt_pk_bf16_f32 v29, v29, v29
	global_store_short v[78:79], v26, off
	global_store_short v[78:79], v27, off offset:1024
	global_store_short v[78:79], v28, off offset:2048
	global_store_short v[78:79], v29, off offset:3072
	v_or_b32_e32 v0, 24, v62
	v_lshlrev_b64 v[78:79], 10, v[0:1]
	v_lshl_add_u64 v[78:79], v[70:71], 0, v[78:79]
	v_cvt_pk_bf16_f32 v30, v30, v30
	v_cvt_pk_bf16_f32 v31, v31, v31
	v_cvt_pk_bf16_f32 v32, v32, v32
	v_cvt_pk_bf16_f32 v33, v33, v33
	global_store_short v[78:79], v30, off
	global_store_short v[78:79], v31, off offset:1024
	global_store_short v[78:79], v32, off offset:2048
	global_store_short v[78:79], v33, off offset:3072
	s_nop 0
	ds_bpermute_b32 v18, v63, v57
	ds_bpermute_b32 v19, v63, v61
	ds_bpermute_b32 v20, v63, v87
	ds_bpermute_b32 v21, v63, v88
	ds_bpermute_b32 v22, v63, v89
	ds_bpermute_b32 v23, v63, v90
	ds_bpermute_b32 v24, v63, v91
	ds_bpermute_b32 v25, v63, v92
	ds_bpermute_b32 v26, v63, v93
	ds_bpermute_b32 v27, v63, v94
	ds_bpermute_b32 v28, v63, v95
	ds_bpermute_b32 v29, v63, v96
	s_waitcnt lgkmcnt(8)
; __device__ __forceinline__ float sum32(float v) { v = dpp_row_sum16(v); v += __shfl_xor(v, 16); return v; }
; __device__ __forceinline__ void seq_item(const Params& p, int item, char* smem, const bool write_o = true) {
;     ...
;         float sq = sum32(o[e] * o[e]);
;         if (r == 0) SSQO[((size_t)(tok0 + t) * 4 + h) * 4 + sl] = sq;
;       }
;     }
; #pragma unroll
;     for (int e = 0; e < 16; e++) S[e] *= dvn;
; #pragma unroll
;     for (int ks = 0; ks < 4; ks++) {
;       bf16x8 a = *(const bf16x8*)&VTs[r * 72 + ks * 16 + hh];
;       S = mfma16(a, ktf[ks], S);
;     }
;     if (m == 1) {
; #pragma unroll
;       for (int ks = 0; ks < 8; ks++) {
;         bf16x8 a = *(const bf16x8*)&STs[r * 136 + ks * 16 + hh];
;         S = mfma16(a, pnf[ks], S);
;       }
;     }
	ds_bpermute_b32 v30, v63, v97
	ds_bpermute_b32 v31, v63, v98
	ds_bpermute_b32 v32, v63, v99
	ds_bpermute_b32 v33, v63, v100
	s_waitcnt lgkmcnt(0)
	v_add_f32_e32 v57, v57, v18
	v_add_f32_e32 v61, v61, v19
	v_add_f32_e32 v87, v87, v20
	v_add_f32_e32 v88, v88, v21
	v_add_f32_e32 v89, v89, v22
	v_add_f32_e32 v90, v90, v23
	v_add_f32_e32 v91, v91, v24
	v_add_f32_e32 v92, v92, v25
	v_add_f32_e32 v93, v93, v26
	v_add_f32_e32 v94, v94, v27
	v_add_f32_e32 v95, v95, v28
	v_add_f32_e32 v96, v96, v29
	v_add_f32_e32 v97, v97, v30
	v_add_f32_e32 v98, v98, v31
	v_add_f32_e32 v99, v99, v32
	v_add_f32_e32 v100, v100, v33
	s_and_b64 exec, exec, s[8:9]
	v_mov_b32_e32 v0, v62
	v_lshlrev_b64 v[78:79], 6, v[0:1]
	v_lshl_add_u64 v[78:79], s[18:19], 0, v[78:79]
	global_store_dword v[78:79], v57, off
	global_store_dword v[78:79], v61, off offset:64
	global_store_dword v[78:79], v87, off offset:128
	global_store_dword v[78:79], v88, off offset:192
	v_or_b32_e32 v0, 8, v62
	v_lshlrev_b64 v[78:79], 6, v[0:1]
	v_lshl_add_u64 v[78:79], s[18:19], 0, v[78:79]
	global_store_dword v[78:79], v89, off
	global_store_dword v[78:79], v90, off offset:64
	global_store_dword v[78:79], v91, off offset:128
	global_store_dword v[78:79], v92, off offset:192
	v_or_b32_e32 v0, 16, v62
	v_lshlrev_b64 v[78:79], 6, v[0:1]
	v_lshl_add_u64 v[78:79], s[18:19], 0, v[78:79]
	global_store_dword v[78:79], v93, off
	global_store_dword v[78:79], v94, off offset:64
	global_store_dword v[78:79], v95, off offset:128
	global_store_dword v[78:79], v96, off offset:192
	v_or_b32_e32 v0, 24, v62
	v_lshlrev_b64 v[78:79], 6, v[0:1]
	v_lshl_add_u64 v[78:79], s[18:19], 0, v[78:79]
	global_store_dword v[78:79], v97, off
	global_store_dword v[78:79], v98, off offset:64
	global_store_dword v[78:79], v99, off offset:128
	global_store_dword v[78:79], v100, off offset:192
.LBB0_1055:
	s_or_b64 exec, exec, s[0:1]
	s_waitcnt lgkmcnt(0)
	ds_read_b128 v[18:21], v80 offset:8704
	ds_read_b128 v[22:25], v80 offset:8736
	v_pk_mul_f32 v[2:3], v[2:3], v[58:59] op_sel_hi:[1,0]
	v_pk_mul_f32 v[16:17], v[16:17], v[58:59] op_sel_hi:[1,0]
	v_pk_mul_f32 v[14:15], v[14:15], v[58:59] op_sel_hi:[1,0]
	v_pk_mul_f32 v[12:13], v[12:13], v[58:59] op_sel_hi:[1,0]
	v_pk_mul_f32 v[10:11], v[10:11], v[58:59] op_sel_hi:[1,0]
	v_pk_mul_f32 v[8:9], v[8:9], v[58:59] op_sel_hi:[1,0]
	v_pk_mul_f32 v[6:7], v[6:7], v[58:59] op_sel_hi:[1,0]
	v_pk_mul_f32 v[4:5], v[4:5], v[58:59] op_sel_hi:[1,0]
	v_cndmask_b32_e64 v0, 0, 1, s[16:17]
	v_accvgpr_write_b32 a0, v2
	v_accvgpr_write_b32 a1, v3
	v_accvgpr_write_b32 a2, v4
	v_accvgpr_write_b32 a3, v5
	v_accvgpr_write_b32 a4, v6
	v_accvgpr_write_b32 a5, v7
	v_accvgpr_write_b32 a6, v8
	v_accvgpr_write_b32 a7, v9
	v_accvgpr_write_b32 a8, v10
	v_accvgpr_write_b32 a9, v11
	v_accvgpr_write_b32 a10, v12
	v_accvgpr_write_b32 a11, v13
	v_accvgpr_write_b32 a12, v14
	v_accvgpr_write_b32 a13, v15
	v_accvgpr_write_b32 a14, v16
	v_accvgpr_write_b32 a15, v17
	ds_read_b128 v[2:5], v80 offset:8768
	ds_read_b128 v[6:9], v80 offset:8800
	s_waitcnt lgkmcnt(3)
	v_mfma_f32_32x32x16_bf16 a[0:15], v[18:21], v[106:109], a[0:15]
	v_cmp_ne_u32_e64 s[0:1], 1, v0
	s_andn2_b64 vcc, exec, s[16:17]
	s_waitcnt lgkmcnt(2)
	v_mfma_f32_32x32x16_bf16 a[0:15], v[22:25], v[110:113], a[0:15]
	s_waitcnt lgkmcnt(1)
	v_mfma_f32_32x32x16_bf16 a[0:15], v[2:5], v[114:117], a[0:15]
	s_waitcnt lgkmcnt(0)
	v_mfma_f32_32x32x16_bf16 a[0:15], v[6:9], v[118:121], a[0:15]
	s_cbranch_vccnz .LBB0_1057
	ds_read_b128 v[2:5], v83
	ds_read_b128 v[6:9], v83 offset:32
	s_waitcnt lgkmcnt(1)
	v_mfma_f32_32x32x16_bf16 a[0:15], v[2:5], v[122:125], a[0:15]
	s_waitcnt lgkmcnt(0)
	v_mfma_f32_32x32x16_bf16 a[0:15], v[6:9], v[126:129], a[0:15]
	ds_read_b128 v[2:5], v83 offset:64
	ds_read_b128 v[6:9], v83 offset:96
	s_waitcnt lgkmcnt(1)
	v_mfma_f32_32x32x16_bf16 a[0:15], v[2:5], v[130:133], a[0:15]
	s_waitcnt lgkmcnt(0)
	v_mfma_f32_32x32x16_bf16 a[0:15], v[6:9], v[134:137], a[0:15]
	ds_read_b128 v[2:5], v83 offset:128
	ds_read_b128 v[6:9], v83 offset:160
	s_waitcnt lgkmcnt(1)
	v_mfma_f32_32x32x16_bf16 a[0:15], v[2:5], v[138:141], a[0:15]
	s_waitcnt lgkmcnt(0)
	v_mfma_f32_32x32x16_bf16 a[0:15], v[6:9], v[142:145], a[0:15]
	ds_read_b128 v[2:5], v83 offset:192
	ds_read_b128 v[6:9], v83 offset:224
	s_waitcnt lgkmcnt(1)
	v_mfma_f32_32x32x16_bf16 a[0:15], v[2:5], v[146:149], a[0:15]
	s_waitcnt lgkmcnt(0)
	v_mfma_f32_32x32x16_bf16 a[0:15], v[6:9], v[150:153], a[0:15]
; __device__ __forceinline__ void seq_item(const Params& p, int item, char* smem, const bool write_o = true) {
;     ...
;     if (n + 1 < 32) SEQ_LOADS(n + 1)
.LBB0_1057:
	s_cmp_eq_u32 s22, 0x1f0000
	s_cbranch_scc1 .LBB0_1021
	s_waitcnt vmcnt(0)
	v_accvgpr_read_b32 v102, a144
	v_accvgpr_read_b32 v103, a145
	v_accvgpr_read_b32 v104, a146
	v_accvgpr_read_b32 v105, a147
	v_accvgpr_read_b32 v58, a148
	v_accvgpr_read_b32 v106, a150
	v_accvgpr_read_b32 v107, a151
	v_accvgpr_read_b32 v108, a152
	v_accvgpr_read_b32 v109, a153
	v_accvgpr_read_b32 v110, a154
	v_accvgpr_read_b32 v111, a155
	v_accvgpr_read_b32 v112, a156
	v_accvgpr_read_b32 v113, a157
	v_accvgpr_read_b32 v114, a158
	v_accvgpr_read_b32 v115, a159
	v_accvgpr_read_b32 v116, a160
	v_accvgpr_read_b32 v117, a161
	v_accvgpr_read_b32 v118, a162
	v_accvgpr_read_b32 v119, a163
	v_accvgpr_read_b32 v120, a164
	v_accvgpr_read_b32 v121, a165
	s_and_b64 s[48:49], exec, s[16:17]
	s_cbranch_scc0 .Lp3_cp_nopn
	v_accvgpr_read_b32 v122, a166
	v_accvgpr_read_b32 v123, a167
	v_accvgpr_read_b32 v124, a168
	v_accvgpr_read_b32 v125, a169
	v_accvgpr_read_b32 v126, a170
	v_accvgpr_read_b32 v127, a171
	v_accvgpr_read_b32 v128, a172
	v_accvgpr_read_b32 v129, a173
	v_accvgpr_read_b32 v130, a174
	v_accvgpr_read_b32 v131, a175
	v_accvgpr_read_b32 v132, a176
	v_accvgpr_read_b32 v133, a177
	v_accvgpr_read_b32 v134, a178
	v_accvgpr_read_b32 v135, a179
	v_accvgpr_read_b32 v136, a180
	v_accvgpr_read_b32 v137, a181
	v_accvgpr_read_b32 v138, a182
	v_accvgpr_read_b32 v139, a183
	v_accvgpr_read_b32 v140, a184
	v_accvgpr_read_b32 v141, a185
	v_accvgpr_read_b32 v142, a186
	v_accvgpr_read_b32 v143, a187
	v_accvgpr_read_b32 v144, a188
	v_accvgpr_read_b32 v145, a189
	v_accvgpr_read_b32 v146, a190
	v_accvgpr_read_b32 v147, a191
	v_accvgpr_read_b32 v148, a192
	v_accvgpr_read_b32 v149, a193
	v_accvgpr_read_b32 v150, a194
	v_accvgpr_read_b32 v151, a195
	v_accvgpr_read_b32 v152, a196
	v_accvgpr_read_b32 v153, a197
.Lp3_cp_nopn:
	s_and_b64 s[48:49], exec, s[4:5]
	s_cbranch_scc0 .LBB0_1021
	v_accvgpr_read_b32 v154, a198
	v_accvgpr_read_b32 v155, a199
	v_accvgpr_read_b32 v156, a200
	v_accvgpr_read_b32 v157, a201
	v_accvgpr_read_b32 v158, a202
	v_accvgpr_read_b32 v159, a203
	v_accvgpr_read_b32 v160, a204
	v_accvgpr_read_b32 v161, a205
	v_accvgpr_read_b32 v162, a206
	v_accvgpr_read_b32 v163, a207
	v_accvgpr_read_b32 v164, a208
	v_accvgpr_read_b32 v165, a209
	v_accvgpr_read_b32 v166, a210
	v_accvgpr_read_b32 v167, a211
	v_accvgpr_read_b32 v168, a212
	v_accvgpr_read_b32 v169, a213
	v_accvgpr_read_b32 v170, a214
	v_accvgpr_read_b32 v171, a215
	v_accvgpr_read_b32 v172, a216
	v_accvgpr_read_b32 v173, a217
	v_accvgpr_read_b32 v174, a218
	v_accvgpr_read_b32 v175, a219
	v_accvgpr_read_b32 v176, a220
	v_accvgpr_read_b32 v177, a221
	v_accvgpr_read_b32 v178, a222
	v_accvgpr_read_b32 v179, a223
	v_accvgpr_read_b32 v180, a224
	v_accvgpr_read_b32 v181, a225
	v_accvgpr_read_b32 v182, a226
	v_accvgpr_read_b32 v183, a227
	v_accvgpr_read_b32 v184, a228
	v_accvgpr_read_b32 v185, a229
	v_accvgpr_read_b32 v57, a230
	v_accvgpr_read_b32 v61, a231
	v_accvgpr_read_b32 v87, a232
	v_accvgpr_read_b32 v88, a233
	v_accvgpr_read_b32 v89, a234
	v_accvgpr_read_b32 v90, a235
	v_accvgpr_read_b32 v91, a236
	v_accvgpr_read_b32 v92, a237
	v_accvgpr_read_b32 v93, a238
	v_accvgpr_read_b32 v94, a239
	v_accvgpr_read_b32 v95, a240
	v_accvgpr_read_b32 v96, a241
	v_accvgpr_read_b32 v97, a242
	v_accvgpr_read_b32 v98, a243
	v_accvgpr_read_b32 v99, a244
	v_accvgpr_read_b32 v100, a245
	s_branch .LBB0_1021

; __device__ __forceinline__ void phase5(const Params& p, char* smem, const bool store_x = true) {
;     ...
;       for (int sl = 0; sl < 7; sl++) {
;         if (key[sl] >= m) {
;           int pos = atomicAdd(&wcnt[hd], 1);
;           int ia = ti[ij[sl] >> 4], ib = ti[16 + (ij[sl] & 15)];
;           widx[hd * 16 + pos] = ia * 128 + ib;
;           wgate[hd * 16 + pos] = ev[sl] * inv;
;         }
;       }
.LBB0_1496:
	s_or_b64 exec, exec, s[18:19]
	v_mbcnt_lo_u32_b32 v0, -1, 0
	v_mbcnt_hi_u32_b32 v0, -1, v0
	v_lshl_add_u32 v1, v0, 3, v176
	ds_read_b64 v[2:3], v1
	ds_read_b64 v[4:5], v1 offset:512
	s_add_u32 s98, s80, 0x3bb5000
	s_addc_u32 s99, s81, 0
	v_lshl_add_u32 v6, v0, 3, v200
	v_lshrrev_b32_e32 v7, 8, v200
	v_add_u32_e32 v7, 0x1100000, v7
	v_mov_b32_e32 v20, 0
	s_waitcnt lgkmcnt(0)
	v_lshlrev_b32_e32 v16, 7, v2
	v_lshlrev_b32_e32 v17, 7, v3
	global_store_dwordx2 v6, v[16:17], s[98:99]
	global_store_dwordx2 v6, v[4:5], s[98:99] offset:512
	s_mov_b64 exec, 1
	global_store_dword v7, v20, s[98:99]
	s_mov_b64 exec, -1
	s_waitcnt vmcnt(3)
	s_and_b64 vcc, exec, s[34:35]
	s_cbranch_vccnz .Lp5a_done
	s_branch .LBB0_1482
